# MLA loops: K fragments read straight into MFMA operand registers via dead v252:253, 4 v_mov per iteration removed
# speedup vs baseline: 1.0077x; 1.0077x over previous
.LBB0_710:
	s_mov_b32 s35, s4
	s_mov_b32 s4, s52
	global_load_dwordx4 v[204:207], v192, s[98:99] offset:128
	global_load_dwordx4 v[208:211], v188, s[98:99]
	global_load_dwordx2 v[218:219], v214, s[98:99] offset:-2048
	ds_read_b128 v[118:121], v199 offset:17424
	ds_read_b128 v[114:117], v199 offset:17408
	ds_read_b128 v[130:133], v199 offset:22016
	ds_read_b128 v[134:137], v199 offset:22032
	ds_read_b128 v[242:245], v199 offset:17488
	ds_read_b128 v[238:241], v199 offset:17472
	s_waitcnt lgkmcnt(4)
	v_add_f32_e32 v160, v86, v82
	v_mfma_scale_f32_32x32x64_f8f6f4 v[114:129], v[114:119], v[168:173], v[50:65], v120, v194 op_sel_hi:[0,0,0] cbsz:2 blgp:2
	v_cvt_pk_fp8_f32 v154, v82, v83
	v_cvt_pk_fp8_f32 v155, v98, v99
	v_cvt_pk_fp8_f32 v154, v84, v85 op_sel:[0,0,1]
	v_cvt_pk_fp8_f32 v155, v100, v101 op_sel:[0,0,1]
	v_add_f32_e32 v82, v87, v83
	v_add_f32_e32 v83, v88, v84
	v_permlane32_swap_b32_e32 v154, v155
	ds_read_b128 v[246:249], v199 offset:22080
	ds_read_b128 v[250:253], v199 offset:22096
	v_add_f32_e32 v84, v89, v85
	s_waitcnt lgkmcnt(3)
	v_mfma_scale_f32_32x32x64_f8f6f4 v[130:145], v[130:135], v[168:173], v[50:65], v136, v194 op_sel_hi:[0,0,0] cbsz:2 blgp:2
	v_add_f32_e32 v85, v90, v160
	v_add_f32_e32 v82, v91, v82
	v_add_f32_e32 v83, v92, v83
	v_add_f32_e32 v84, v93, v84
	v_add_f32_e32 v159, v94, v85
	v_add_f32_e32 v160, v95, v82
	v_add_f32_e32 v161, v96, v83
	v_add_f32_e32 v186, v97, v84
	ds_read_b128 v[230:233], v222 offset:5120
	ds_read_b128 v[234:237], v222 offset:5136
	s_waitcnt lgkmcnt(4)
	v_mfma_scale_f32_32x32x64_f8f6f4 v[114:129], v[238:243], v[162:167], v[114:129], v244, v190 op_sel_hi:[0,0,0] cbsz:2 blgp:2
	v_cvt_pk_fp8_f32 v156, v86, v87
	v_cvt_pk_fp8_f32 v157, v102, v103
	v_cvt_pk_fp8_f32 v156, v88, v89 op_sel:[0,0,1]
	v_cvt_pk_fp8_f32 v157, v104, v105 op_sel:[0,0,1]
	v_add_f32_e32 v98, v98, v159
	v_add_f32_e32 v99, v99, v160
	v_permlane32_swap_b32_e32 v156, v157
	v_add_f32_e32 v100, v100, v161
	v_add_f32_e32 v101, v101, v186
	v_add_f32_e32 v98, v102, v98
	ds_read_b128 v[82:85], v222 offset:7680
	ds_read_b128 v[86:89], v222 offset:7696
	s_waitcnt lgkmcnt(4)
	v_mfma_scale_f32_32x32x64_f8f6f4 v[130:145], v[246:251], v[162:167], v[130:145], v252, v190 op_sel_hi:[0,0,0] cbsz:2 blgp:2
	v_cvt_pk_fp8_f32 v158, v90, v91
	v_cvt_pk_fp8_f32 v159, v106, v107
	v_cvt_pk_fp8_f32 v158, v92, v93 op_sel:[0,0,1]
	v_cvt_pk_fp8_f32 v159, v108, v109 op_sel:[0,0,1]
	v_add_f32_e32 v90, v103, v99
	v_add_f32_e32 v91, v104, v100
	v_permlane32_swap_b32_e32 v158, v159
	v_add_f32_e32 v92, v105, v101
	s_waitcnt lgkmcnt(2)
	v_mfma_scale_f32_32x32x64_f8f6f4 v[114:129], v[230:237], v[146:153], v[114:129], v220, v1 op_sel_hi:[0,0,0]
	v_add_f32_e32 v93, v106, v98
	v_add_f32_e32 v90, v107, v90
	v_add_f32_e32 v91, v108, v91
	v_add_f32_e32 v92, v109, v92
	v_add_f32_e32 v93, v110, v93
	v_add_f32_e32 v90, v111, v90
	v_add_f32_e32 v91, v112, v91
	v_add_f32_e32 v92, v113, v92
	v_cvt_pk_fp8_f32 v160, v94, v95
	v_cvt_pk_fp8_f32 v161, v110, v111
	v_cvt_pk_fp8_f32 v160, v96, v97 op_sel:[0,0,1]
	v_cvt_pk_fp8_f32 v161, v112, v113 op_sel:[0,0,1]
	s_waitcnt lgkmcnt(0)
	v_mfma_scale_f32_32x32x64_f8f6f4 v[130:145], v[82:89], v[146:153], v[130:145], v220, v1 op_sel_hi:[0,0,0]
	v_add_f32_e32 v82, v93, v90
	v_add_f32_e32 v83, v91, v92
	v_permlane32_swap_b32_e32 v160, v161
	v_add_f32_e32 v229, v82, v83
	v_mov_b32_e32 v230, v229
	v_add_u32_e32 v82, s5, v224
	s_waitcnt vmcnt(0)
	ds_write_b128 v82, v[204:207]
	ds_write_b128 v225, v[208:211] offset:49152
	ds_write_b64 v226, v[218:219]
	v_add_u32_e32 v98, s4, v191
	ds_read_b128 v[90:93], v98
	ds_read_b128 v[94:97], v98 offset:16
	v_max3_f32 v82, v114, s88, v115
	v_max3_f32 v82, v82, v116, v117
	v_max3_f32 v82, v82, v118, v119
	v_permlane32_swap_b32_e32 v229, v230
	v_max3_f32 v99, v82, v120, v121
	ds_read_b128 v[82:85], v98 offset:2560
	ds_read_b128 v[86:89], v98 offset:2576
	v_max3_f32 v99, v99, v122, v123
	v_max3_f32 v99, v99, v124, v125
	v_max3_f32 v99, v99, v126, v127
	v_max3_f32 v99, v99, v128, v129
	s_waitcnt lgkmcnt(2)
	v_mfma_scale_f32_32x32x64_f8f6f4 v[66:81], v[90:97], v[154:161], v[66:81], v220, v220 op_sel_hi:[0,0,0]
	v_max3_f32 v99, v99, v130, v131
	v_max3_f32 v99, v99, v132, v133
	v_max3_f32 v99, v99, v134, v135
	v_max3_f32 v99, v99, v136, v137
	v_max3_f32 v99, v99, v138, v139
	v_max3_f32 v99, v99, v140, v141
	v_max3_f32 v99, v99, v142, v143
	v_max3_f32 v99, v99, v144, v145
	v_mov_b32_e32 v100, v99
	v_mov_b32_e32 v186, 1.0
	s_nop 0
	v_permlane32_swap_b32_e32 v99, v100
	v_max_f32_e32 v99, v99, v100
	v_cmp_ge_f32_e32 vcc, s89, v99
	s_cmp_eq_u64 vcc, exec
	s_cbranch_scc1 .LBB0_712
	v_add_f32_e32 v99, -4.0, v99
	v_max_f32_e32 v99, 0, v99
	v_exp_f32_e64 v186, -v99
	v_sub_f32_e32 v129, v129, v99
	v_sub_f32_e32 v128, v128, v99
	v_sub_f32_e32 v127, v127, v99
	v_sub_f32_e32 v126, v126, v99
	v_sub_f32_e32 v125, v125, v99
	v_sub_f32_e32 v124, v124, v99
	v_sub_f32_e32 v123, v123, v99
	v_sub_f32_e32 v122, v122, v99
	v_sub_f32_e32 v121, v121, v99
	v_sub_f32_e32 v120, v120, v99
	v_sub_f32_e32 v119, v119, v99
	v_sub_f32_e32 v118, v118, v99
	v_sub_f32_e32 v117, v117, v99
	v_sub_f32_e32 v116, v116, v99
	v_sub_f32_e32 v115, v115, v99
	v_sub_f32_e32 v114, v114, v99
	v_sub_f32_e32 v145, v145, v99
	v_sub_f32_e32 v144, v144, v99
	v_sub_f32_e32 v143, v143, v99
	v_sub_f32_e32 v142, v142, v99
	v_sub_f32_e32 v141, v141, v99
	v_sub_f32_e32 v140, v140, v99
	v_sub_f32_e32 v139, v139, v99
	v_sub_f32_e32 v138, v138, v99
	v_sub_f32_e32 v137, v137, v99
	v_sub_f32_e32 v136, v136, v99
	v_sub_f32_e32 v135, v135, v99
	v_sub_f32_e32 v134, v134, v99
	v_sub_f32_e32 v133, v133, v99
	v_sub_f32_e32 v132, v132, v99
	v_sub_f32_e32 v131, v131, v99
	v_sub_f32_e32 v130, v130, v99
	v_sub_f32_e32 v65, v65, v99
	v_sub_f32_e32 v64, v64, v99
	v_sub_f32_e32 v63, v63, v99
	v_sub_f32_e32 v62, v62, v99
	v_sub_f32_e32 v61, v61, v99
	v_sub_f32_e32 v60, v60, v99
	v_sub_f32_e32 v59, v59, v99
	v_sub_f32_e32 v58, v58, v99
	v_sub_f32_e32 v57, v57, v99
	v_sub_f32_e32 v56, v56, v99
	v_sub_f32_e32 v55, v55, v99
	v_sub_f32_e32 v54, v54, v99
	v_sub_f32_e32 v53, v53, v99
	v_sub_f32_e32 v52, v52, v99
	v_sub_f32_e32 v51, v51, v99
	v_sub_f32_e32 v50, v50, v99

.LBB0_714:
	s_barrier
	global_load_dwordx4 v[204:207], v192, s[98:99] offset:192
	global_load_dwordx4 v[208:211], v189, s[98:99]
	global_load_dwordx2 v[196:197], v214, s[98:99] offset:2048
	ds_read_b128 v[86:89], v223 offset:49168
	ds_read_b128 v[82:85], v223 offset:49152
	ds_read_b128 v[98:101], v223 offset:53760
	ds_read_b128 v[102:105], v223 offset:53776
	ds_read_b128 v[156:159], v223 offset:49232
	ds_read_b128 v[240:243], v223 offset:49216
	s_waitcnt lgkmcnt(4)
	v_add_f32_e32 v160, v118, v114
	v_mfma_scale_f32_32x32x64_f8f6f4 v[82:97], v[82:87], v[174:179], v[50:65], v88, v198 op_sel_hi:[0,0,0] cbsz:2 blgp:2
	v_cvt_pk_fp8_f32 v154, v114, v115
	v_cvt_pk_fp8_f32 v155, v130, v131
	v_cvt_pk_fp8_f32 v154, v116, v117 op_sel:[0,0,1]
	v_cvt_pk_fp8_f32 v155, v132, v133 op_sel:[0,0,1]
	v_add_f32_e32 v114, v119, v115
	v_add_f32_e32 v115, v120, v116
	v_permlane32_swap_b32_e32 v154, v155
	ds_read_b128 v[246:249], v223 offset:53824
	ds_read_b128 v[250:253], v223 offset:53840
	v_add_f32_e32 v116, v121, v117
	s_waitcnt lgkmcnt(3)
	v_mfma_scale_f32_32x32x64_f8f6f4 v[98:113], v[98:103], v[174:179], v[50:65], v104, v198 op_sel_hi:[0,0,0] cbsz:2 blgp:2
	v_add_f32_e32 v117, v122, v160
	v_add_f32_e32 v114, v123, v114
	v_mov_b32_e32 v244, v156
	v_mov_b32_e32 v245, v157
	v_add_f32_e32 v115, v124, v115
	v_add_f32_e32 v116, v125, v116
	v_add_f32_e32 v159, v126, v117
	v_add_f32_e32 v160, v127, v114
	v_add_f32_e32 v161, v128, v115
	v_add_f32_e32 v200, v129, v116
	ds_read_b128 v[232:235], v222
	ds_read_b128 v[236:239], v222 offset:16
	s_waitcnt lgkmcnt(4)
	v_mfma_scale_f32_32x32x64_f8f6f4 v[82:97], v[240:245], v[180:185], v[82:97], v158, v202 op_sel_hi:[0,0,0] cbsz:2 blgp:2
	v_cvt_pk_fp8_f32 v156, v118, v119
	v_cvt_pk_fp8_f32 v157, v134, v135
	v_cvt_pk_fp8_f32 v156, v120, v121 op_sel:[0,0,1]
	v_cvt_pk_fp8_f32 v157, v136, v137 op_sel:[0,0,1]
	v_add_f32_e32 v130, v130, v159
	v_add_f32_e32 v131, v131, v160
	v_permlane32_swap_b32_e32 v156, v157
	s_waitcnt lgkmcnt(2)
	v_add_f32_e32 v132, v132, v161
	v_add_f32_e32 v133, v133, v200
	v_add_f32_e32 v130, v134, v130
	ds_read_b128 v[114:117], v222 offset:2560
	ds_read_b128 v[118:121], v222 offset:2576
	v_mfma_scale_f32_32x32x64_f8f6f4 v[98:113], v[246:251], v[180:185], v[98:113], v252, v202 op_sel_hi:[0,0,0] cbsz:2 blgp:2
	v_cvt_pk_fp8_f32 v158, v122, v123
	v_cvt_pk_fp8_f32 v159, v138, v139
	v_cvt_pk_fp8_f32 v158, v124, v125 op_sel:[0,0,1]
	v_cvt_pk_fp8_f32 v159, v140, v141 op_sel:[0,0,1]
	v_add_f32_e32 v122, v135, v131
	v_add_f32_e32 v123, v136, v132
	v_permlane32_swap_b32_e32 v158, v159
	v_add_f32_e32 v124, v137, v133
	s_waitcnt lgkmcnt(2)
	v_mfma_scale_f32_32x32x64_f8f6f4 v[82:97], v[232:239], v[146:153], v[82:97], v220, v1 op_sel_hi:[0,0,0]
	v_add_f32_e32 v125, v138, v130
	v_add_f32_e32 v122, v139, v122
	v_add_f32_e32 v123, v140, v123
	v_add_f32_e32 v124, v141, v124
	v_add_f32_e32 v125, v142, v125
	v_add_f32_e32 v122, v143, v122
	v_add_f32_e32 v123, v144, v123
	v_add_f32_e32 v124, v145, v124
	v_cvt_pk_fp8_f32 v160, v126, v127
	v_cvt_pk_fp8_f32 v161, v142, v143
	v_cvt_pk_fp8_f32 v160, v128, v129 op_sel:[0,0,1]
	v_cvt_pk_fp8_f32 v161, v144, v145 op_sel:[0,0,1]
	s_waitcnt lgkmcnt(0)
	v_mfma_scale_f32_32x32x64_f8f6f4 v[98:113], v[114:121], v[146:153], v[98:113], v220, v1 op_sel_hi:[0,0,0]
	v_add_f32_e32 v114, v125, v122
	v_add_f32_e32 v115, v123, v124
	v_permlane32_swap_b32_e32 v160, v161
	v_add_f32_e32 v130, v114, v115
	v_mov_b32_e32 v131, v130
	v_add_u32_e32 v114, s4, v224
	s_waitcnt vmcnt(0)
	ds_write_b128 v114, v[204:207]
	ds_write_b128 v203, v[208:211]
	ds_write_b64 v227, v[196:197]
	v_add_u32_e32 v132, s35, v191
	ds_read_b128 v[122:125], v132
	ds_read_b128 v[126:129], v132 offset:16
	v_max3_f32 v114, v82, s88, v83
	v_max3_f32 v114, v114, v84, v85
	v_max3_f32 v114, v114, v86, v87
	v_permlane32_swap_b32_e32 v130, v131
	v_max3_f32 v133, v114, v88, v89
	ds_read_b128 v[114:117], v132 offset:2560
	ds_read_b128 v[118:121], v132 offset:2576
	v_max3_f32 v133, v133, v90, v91
	v_max3_f32 v133, v133, v92, v93
	v_max3_f32 v133, v133, v94, v95
	v_max3_f32 v133, v133, v96, v97
	s_waitcnt lgkmcnt(2)
	v_mfma_scale_f32_32x32x64_f8f6f4 v[66:81], v[122:129], v[154:161], v[66:81], v220, v220 op_sel_hi:[0,0,0]
	v_max3_f32 v133, v133, v98, v99
	v_max3_f32 v133, v133, v100, v101
	v_max3_f32 v133, v133, v102, v103
	v_max3_f32 v133, v133, v104, v105
	v_max3_f32 v133, v133, v106, v107
	v_max3_f32 v133, v133, v108, v109
	v_max3_f32 v133, v133, v110, v111
	v_max3_f32 v133, v133, v112, v113
	v_mov_b32_e32 v134, v133
	v_mov_b32_e32 v138, 1.0
	s_nop 0
	v_permlane32_swap_b32_e32 v133, v134
	v_max_f32_e32 v133, v133, v134
	v_cmp_ge_f32_e32 vcc, s89, v133
	s_cmp_eq_u64 vcc, exec
	s_cbranch_scc1 .LBB0_716
	v_add_f32_e32 v133, -4.0, v133
	v_max_f32_e32 v133, 0, v133
	v_exp_f32_e64 v138, -v133
	v_sub_f32_e32 v97, v97, v133
	v_sub_f32_e32 v96, v96, v133
	v_sub_f32_e32 v95, v95, v133
	v_sub_f32_e32 v94, v94, v133
	v_sub_f32_e32 v93, v93, v133
	v_sub_f32_e32 v92, v92, v133
	v_sub_f32_e32 v91, v91, v133
	v_sub_f32_e32 v90, v90, v133
	v_sub_f32_e32 v89, v89, v133
	v_sub_f32_e32 v88, v88, v133
	v_sub_f32_e32 v87, v87, v133
	v_sub_f32_e32 v86, v86, v133
	v_sub_f32_e32 v85, v85, v133
	v_sub_f32_e32 v84, v84, v133
	v_sub_f32_e32 v83, v83, v133
	v_sub_f32_e32 v82, v82, v133
	v_sub_f32_e32 v113, v113, v133
	v_sub_f32_e32 v112, v112, v133
	v_sub_f32_e32 v111, v111, v133
	v_sub_f32_e32 v110, v110, v133
	v_sub_f32_e32 v109, v109, v133
	v_sub_f32_e32 v108, v108, v133
	v_sub_f32_e32 v107, v107, v133
	v_sub_f32_e32 v106, v106, v133
	v_sub_f32_e32 v105, v105, v133
	v_sub_f32_e32 v104, v104, v133
	v_sub_f32_e32 v103, v103, v133
	v_sub_f32_e32 v102, v102, v133
	v_sub_f32_e32 v101, v101, v133
	v_sub_f32_e32 v100, v100, v133
	v_sub_f32_e32 v99, v99, v133
	v_sub_f32_e32 v98, v98, v133
	v_sub_f32_e32 v65, v65, v133
	v_sub_f32_e32 v64, v64, v133
	v_sub_f32_e32 v63, v63, v133
	v_sub_f32_e32 v62, v62, v133
	v_sub_f32_e32 v61, v61, v133
	v_sub_f32_e32 v60, v60, v133
	v_sub_f32_e32 v59, v59, v133
	v_sub_f32_e32 v58, v58, v133
	v_sub_f32_e32 v57, v57, v133
	v_sub_f32_e32 v56, v56, v133
	v_sub_f32_e32 v55, v55, v133
	v_sub_f32_e32 v54, v54, v133
	v_sub_f32_e32 v53, v53, v133
	v_sub_f32_e32 v52, v52, v133
	v_sub_f32_e32 v51, v51, v133
	v_sub_f32_e32 v50, v50, v133

.LBB0_1733:
	s_mov_b32 s10, s4
	s_mov_b32 s4, s8
	global_load_dwordx4 v[204:207], v192, s[98:99] offset:128
	global_load_dwordx4 v[208:211], v188, s[98:99]
	global_load_dwordx2 v[218:219], v214, s[98:99] offset:-2048
	ds_read_b128 v[118:121], v199 offset:17424
	ds_read_b128 v[114:117], v199 offset:17408
	ds_read_b128 v[130:133], v199 offset:22016
	ds_read_b128 v[134:137], v199 offset:22032
	ds_read_b128 v[242:245], v199 offset:17488
	ds_read_b128 v[238:241], v199 offset:17472
	s_waitcnt lgkmcnt(4)
	v_add_f32_e32 v160, v86, v82
	v_mfma_scale_f32_32x32x64_f8f6f4 v[114:129], v[114:119], v[168:173], v[50:65], v120, v194 op_sel_hi:[0,0,0] cbsz:2 blgp:2
	v_cvt_pk_fp8_f32 v154, v82, v83
	v_cvt_pk_fp8_f32 v155, v98, v99
	v_cvt_pk_fp8_f32 v154, v84, v85 op_sel:[0,0,1]
	v_cvt_pk_fp8_f32 v155, v100, v101 op_sel:[0,0,1]
	v_add_f32_e32 v82, v87, v83
	v_add_f32_e32 v83, v88, v84
	v_permlane32_swap_b32_e32 v154, v155
	ds_read_b128 v[246:249], v199 offset:22080
	ds_read_b128 v[250:253], v199 offset:22096
	v_add_f32_e32 v84, v89, v85
	s_waitcnt lgkmcnt(3)
	v_mfma_scale_f32_32x32x64_f8f6f4 v[130:145], v[130:135], v[168:173], v[50:65], v136, v194 op_sel_hi:[0,0,0] cbsz:2 blgp:2
	v_add_f32_e32 v85, v90, v160
	v_add_f32_e32 v82, v91, v82
	v_add_f32_e32 v83, v92, v83
	v_add_f32_e32 v84, v93, v84
	v_add_f32_e32 v159, v94, v85
	v_add_f32_e32 v160, v95, v82
	v_add_f32_e32 v161, v96, v83
	v_add_f32_e32 v186, v97, v84
	ds_read_b128 v[230:233], v222 offset:5120
	ds_read_b128 v[234:237], v222 offset:5136
	s_waitcnt lgkmcnt(4)
	v_mfma_scale_f32_32x32x64_f8f6f4 v[114:129], v[238:243], v[162:167], v[114:129], v244, v190 op_sel_hi:[0,0,0] cbsz:2 blgp:2
	v_cvt_pk_fp8_f32 v156, v86, v87
	v_cvt_pk_fp8_f32 v157, v102, v103
	v_cvt_pk_fp8_f32 v156, v88, v89 op_sel:[0,0,1]
	v_cvt_pk_fp8_f32 v157, v104, v105 op_sel:[0,0,1]
	v_add_f32_e32 v98, v98, v159
	v_add_f32_e32 v99, v99, v160
	v_permlane32_swap_b32_e32 v156, v157
	v_add_f32_e32 v100, v100, v161
	v_add_f32_e32 v101, v101, v186
	v_add_f32_e32 v98, v102, v98
	ds_read_b128 v[82:85], v222 offset:7680
	ds_read_b128 v[86:89], v222 offset:7696
	s_waitcnt lgkmcnt(4)
	v_mfma_scale_f32_32x32x64_f8f6f4 v[130:145], v[246:251], v[162:167], v[130:145], v252, v190 op_sel_hi:[0,0,0] cbsz:2 blgp:2
	v_cvt_pk_fp8_f32 v158, v90, v91
	v_cvt_pk_fp8_f32 v159, v106, v107
	v_cvt_pk_fp8_f32 v158, v92, v93 op_sel:[0,0,1]
	v_cvt_pk_fp8_f32 v159, v108, v109 op_sel:[0,0,1]
	v_add_f32_e32 v90, v103, v99
	v_add_f32_e32 v91, v104, v100
	v_permlane32_swap_b32_e32 v158, v159
	v_add_f32_e32 v92, v105, v101
	s_waitcnt lgkmcnt(2)
	v_mfma_scale_f32_32x32x64_f8f6f4 v[114:129], v[230:237], v[146:153], v[114:129], v220, v1 op_sel_hi:[0,0,0]
	v_add_f32_e32 v93, v106, v98
	v_add_f32_e32 v90, v107, v90
	v_add_f32_e32 v91, v108, v91
	v_add_f32_e32 v92, v109, v92
	v_add_f32_e32 v93, v110, v93
	v_add_f32_e32 v90, v111, v90
	v_add_f32_e32 v91, v112, v91
	v_add_f32_e32 v92, v113, v92
	v_cvt_pk_fp8_f32 v160, v94, v95
	v_cvt_pk_fp8_f32 v161, v110, v111
	v_cvt_pk_fp8_f32 v160, v96, v97 op_sel:[0,0,1]
	v_cvt_pk_fp8_f32 v161, v112, v113 op_sel:[0,0,1]
	s_waitcnt lgkmcnt(0)
	v_mfma_scale_f32_32x32x64_f8f6f4 v[130:145], v[82:89], v[146:153], v[130:145], v220, v1 op_sel_hi:[0,0,0]
	v_add_f32_e32 v82, v93, v90
	v_add_f32_e32 v83, v91, v92
	v_permlane32_swap_b32_e32 v160, v161
	v_add_f32_e32 v229, v82, v83
	v_mov_b32_e32 v230, v229
	v_add_u32_e32 v82, s5, v224
	s_waitcnt vmcnt(0)
	ds_write_b128 v82, v[204:207]
	ds_write_b128 v225, v[208:211] offset:49152
	ds_write_b64 v226, v[218:219]
	v_add_u32_e32 v98, s4, v191
	ds_read_b128 v[90:93], v98
	ds_read_b128 v[94:97], v98 offset:16
	v_max3_f32 v82, v114, s87, v115
	v_max3_f32 v82, v82, v116, v117
	v_max3_f32 v82, v82, v118, v119
	v_permlane32_swap_b32_e32 v229, v230
	v_max3_f32 v99, v82, v120, v121
	ds_read_b128 v[82:85], v98 offset:2560
	ds_read_b128 v[86:89], v98 offset:2576
	v_max3_f32 v99, v99, v122, v123
	v_max3_f32 v99, v99, v124, v125
	v_max3_f32 v99, v99, v126, v127
	v_max3_f32 v99, v99, v128, v129
	s_waitcnt lgkmcnt(2)
	v_mfma_scale_f32_32x32x64_f8f6f4 v[66:81], v[90:97], v[154:161], v[66:81], v220, v220 op_sel_hi:[0,0,0]
	v_max3_f32 v99, v99, v130, v131
	v_max3_f32 v99, v99, v132, v133
	v_max3_f32 v99, v99, v134, v135
	v_max3_f32 v99, v99, v136, v137
	v_max3_f32 v99, v99, v138, v139
	v_max3_f32 v99, v99, v140, v141
	v_max3_f32 v99, v99, v142, v143
	v_max3_f32 v99, v99, v144, v145
	v_mov_b32_e32 v100, v99
	v_mov_b32_e32 v186, 1.0
	s_nop 0
	v_permlane32_swap_b32_e32 v99, v100
	v_max_f32_e32 v99, v99, v100
	v_cmp_ge_f32_e32 vcc, s88, v99
	s_cmp_eq_u64 vcc, exec
	s_cbranch_scc1 .LBB0_1735
	v_add_f32_e32 v99, -4.0, v99
	v_max_f32_e32 v99, 0, v99
	v_exp_f32_e64 v186, -v99
	v_sub_f32_e32 v129, v129, v99
	v_sub_f32_e32 v128, v128, v99
	v_sub_f32_e32 v127, v127, v99
	v_sub_f32_e32 v126, v126, v99
	v_sub_f32_e32 v125, v125, v99
	v_sub_f32_e32 v124, v124, v99
	v_sub_f32_e32 v123, v123, v99
	v_sub_f32_e32 v122, v122, v99
	v_sub_f32_e32 v121, v121, v99
	v_sub_f32_e32 v120, v120, v99
	v_sub_f32_e32 v119, v119, v99
	v_sub_f32_e32 v118, v118, v99
	v_sub_f32_e32 v117, v117, v99
	v_sub_f32_e32 v116, v116, v99
	v_sub_f32_e32 v115, v115, v99
	v_sub_f32_e32 v114, v114, v99
	v_sub_f32_e32 v145, v145, v99
	v_sub_f32_e32 v144, v144, v99
	v_sub_f32_e32 v143, v143, v99
	v_sub_f32_e32 v142, v142, v99
	v_sub_f32_e32 v141, v141, v99
	v_sub_f32_e32 v140, v140, v99
	v_sub_f32_e32 v139, v139, v99
	v_sub_f32_e32 v138, v138, v99
	v_sub_f32_e32 v137, v137, v99
	v_sub_f32_e32 v136, v136, v99
	v_sub_f32_e32 v135, v135, v99
	v_sub_f32_e32 v134, v134, v99
	v_sub_f32_e32 v133, v133, v99
	v_sub_f32_e32 v132, v132, v99
	v_sub_f32_e32 v131, v131, v99
	v_sub_f32_e32 v130, v130, v99
	v_sub_f32_e32 v65, v65, v99
	v_sub_f32_e32 v64, v64, v99
	v_sub_f32_e32 v63, v63, v99
	v_sub_f32_e32 v62, v62, v99
	v_sub_f32_e32 v61, v61, v99
	v_sub_f32_e32 v60, v60, v99
	v_sub_f32_e32 v59, v59, v99
	v_sub_f32_e32 v58, v58, v99
	v_sub_f32_e32 v57, v57, v99
	v_sub_f32_e32 v56, v56, v99
	v_sub_f32_e32 v55, v55, v99
	v_sub_f32_e32 v54, v54, v99
	v_sub_f32_e32 v53, v53, v99
	v_sub_f32_e32 v52, v52, v99
	v_sub_f32_e32 v51, v51, v99
	v_sub_f32_e32 v50, v50, v99

.LBB0_1737:
	s_barrier
	global_load_dwordx4 v[204:207], v192, s[98:99] offset:192
	global_load_dwordx4 v[208:211], v189, s[98:99]
	global_load_dwordx2 v[196:197], v214, s[98:99] offset:2048
	ds_read_b128 v[86:89], v223 offset:49168
	ds_read_b128 v[82:85], v223 offset:49152
	ds_read_b128 v[98:101], v223 offset:53760
	ds_read_b128 v[102:105], v223 offset:53776
	ds_read_b128 v[156:159], v223 offset:49232
	ds_read_b128 v[240:243], v223 offset:49216
	s_waitcnt lgkmcnt(4)
	v_add_f32_e32 v160, v118, v114
	v_mfma_scale_f32_32x32x64_f8f6f4 v[82:97], v[82:87], v[174:179], v[50:65], v88, v198 op_sel_hi:[0,0,0] cbsz:2 blgp:2
	v_cvt_pk_fp8_f32 v154, v114, v115
	v_cvt_pk_fp8_f32 v155, v130, v131
	v_cvt_pk_fp8_f32 v154, v116, v117 op_sel:[0,0,1]
	v_cvt_pk_fp8_f32 v155, v132, v133 op_sel:[0,0,1]
	v_add_f32_e32 v114, v119, v115
	v_add_f32_e32 v115, v120, v116
	v_permlane32_swap_b32_e32 v154, v155
	ds_read_b128 v[246:249], v223 offset:53824
	ds_read_b128 v[250:253], v223 offset:53840
	v_add_f32_e32 v116, v121, v117
	s_waitcnt lgkmcnt(3)
	v_mfma_scale_f32_32x32x64_f8f6f4 v[98:113], v[98:103], v[174:179], v[50:65], v104, v198 op_sel_hi:[0,0,0] cbsz:2 blgp:2
	v_add_f32_e32 v117, v122, v160
	v_add_f32_e32 v114, v123, v114
	v_mov_b32_e32 v244, v156
	v_mov_b32_e32 v245, v157
	v_add_f32_e32 v115, v124, v115
	v_add_f32_e32 v116, v125, v116
	v_add_f32_e32 v159, v126, v117
	v_add_f32_e32 v160, v127, v114
	v_add_f32_e32 v161, v128, v115
	v_add_f32_e32 v200, v129, v116
	ds_read_b128 v[232:235], v222
	ds_read_b128 v[236:239], v222 offset:16
	s_waitcnt lgkmcnt(4)
	v_mfma_scale_f32_32x32x64_f8f6f4 v[82:97], v[240:245], v[180:185], v[82:97], v158, v202 op_sel_hi:[0,0,0] cbsz:2 blgp:2
	v_cvt_pk_fp8_f32 v156, v118, v119
	v_cvt_pk_fp8_f32 v157, v134, v135
	v_cvt_pk_fp8_f32 v156, v120, v121 op_sel:[0,0,1]
	v_cvt_pk_fp8_f32 v157, v136, v137 op_sel:[0,0,1]
	v_add_f32_e32 v130, v130, v159
	v_add_f32_e32 v131, v131, v160
	v_permlane32_swap_b32_e32 v156, v157
	s_waitcnt lgkmcnt(2)
	v_add_f32_e32 v132, v132, v161
	v_add_f32_e32 v133, v133, v200
	v_add_f32_e32 v130, v134, v130
	ds_read_b128 v[114:117], v222 offset:2560
	ds_read_b128 v[118:121], v222 offset:2576
	v_mfma_scale_f32_32x32x64_f8f6f4 v[98:113], v[246:251], v[180:185], v[98:113], v252, v202 op_sel_hi:[0,0,0] cbsz:2 blgp:2
	v_cvt_pk_fp8_f32 v158, v122, v123
	v_cvt_pk_fp8_f32 v159, v138, v139
	v_cvt_pk_fp8_f32 v158, v124, v125 op_sel:[0,0,1]
	v_cvt_pk_fp8_f32 v159, v140, v141 op_sel:[0,0,1]
	v_add_f32_e32 v122, v135, v131
	v_add_f32_e32 v123, v136, v132
	v_permlane32_swap_b32_e32 v158, v159
	v_add_f32_e32 v124, v137, v133
	s_waitcnt lgkmcnt(2)
	v_mfma_scale_f32_32x32x64_f8f6f4 v[82:97], v[232:239], v[146:153], v[82:97], v220, v1 op_sel_hi:[0,0,0]
	v_add_f32_e32 v125, v138, v130
	v_add_f32_e32 v122, v139, v122
	v_add_f32_e32 v123, v140, v123
	v_add_f32_e32 v124, v141, v124
	v_add_f32_e32 v125, v142, v125
	v_add_f32_e32 v122, v143, v122
	v_add_f32_e32 v123, v144, v123
	v_add_f32_e32 v124, v145, v124
	v_cvt_pk_fp8_f32 v160, v126, v127
	v_cvt_pk_fp8_f32 v161, v142, v143
	v_cvt_pk_fp8_f32 v160, v128, v129 op_sel:[0,0,1]
	v_cvt_pk_fp8_f32 v161, v144, v145 op_sel:[0,0,1]
	s_waitcnt lgkmcnt(0)
	v_mfma_scale_f32_32x32x64_f8f6f4 v[98:113], v[114:121], v[146:153], v[98:113], v220, v1 op_sel_hi:[0,0,0]
	v_add_f32_e32 v114, v125, v122
	v_add_f32_e32 v115, v123, v124
	v_permlane32_swap_b32_e32 v160, v161
	v_add_f32_e32 v130, v114, v115
	v_mov_b32_e32 v131, v130
	v_add_u32_e32 v114, s4, v224
	s_waitcnt vmcnt(0)
	ds_write_b128 v114, v[204:207]
	ds_write_b128 v203, v[208:211]
	ds_write_b64 v227, v[196:197]
	v_add_u32_e32 v132, s10, v191
	ds_read_b128 v[122:125], v132
	ds_read_b128 v[126:129], v132 offset:16
	v_max3_f32 v114, v82, s87, v83
	v_max3_f32 v114, v114, v84, v85
	v_max3_f32 v114, v114, v86, v87
	v_permlane32_swap_b32_e32 v130, v131
	v_max3_f32 v133, v114, v88, v89
	ds_read_b128 v[114:117], v132 offset:2560
	ds_read_b128 v[118:121], v132 offset:2576
	v_max3_f32 v133, v133, v90, v91
	v_max3_f32 v133, v133, v92, v93
	v_max3_f32 v133, v133, v94, v95
	v_max3_f32 v133, v133, v96, v97
	s_waitcnt lgkmcnt(2)
	v_mfma_scale_f32_32x32x64_f8f6f4 v[66:81], v[122:129], v[154:161], v[66:81], v220, v220 op_sel_hi:[0,0,0]
	v_max3_f32 v133, v133, v98, v99
	v_max3_f32 v133, v133, v100, v101
	v_max3_f32 v133, v133, v102, v103
	v_max3_f32 v133, v133, v104, v105
	v_max3_f32 v133, v133, v106, v107
	v_max3_f32 v133, v133, v108, v109
	v_max3_f32 v133, v133, v110, v111
	v_max3_f32 v133, v133, v112, v113
	v_mov_b32_e32 v134, v133
	v_mov_b32_e32 v138, 1.0
	s_nop 0
	v_permlane32_swap_b32_e32 v133, v134
	v_max_f32_e32 v133, v133, v134
	v_cmp_ge_f32_e32 vcc, s88, v133
	s_cmp_eq_u64 vcc, exec
	s_cbranch_scc1 .LBB0_1739
	v_add_f32_e32 v133, -4.0, v133
	v_max_f32_e32 v133, 0, v133
	v_exp_f32_e64 v138, -v133
	v_sub_f32_e32 v97, v97, v133
	v_sub_f32_e32 v96, v96, v133
	v_sub_f32_e32 v95, v95, v133
	v_sub_f32_e32 v94, v94, v133
	v_sub_f32_e32 v93, v93, v133
	v_sub_f32_e32 v92, v92, v133
	v_sub_f32_e32 v91, v91, v133
	v_sub_f32_e32 v90, v90, v133
	v_sub_f32_e32 v89, v89, v133
	v_sub_f32_e32 v88, v88, v133
	v_sub_f32_e32 v87, v87, v133
	v_sub_f32_e32 v86, v86, v133
	v_sub_f32_e32 v85, v85, v133
	v_sub_f32_e32 v84, v84, v133
	v_sub_f32_e32 v83, v83, v133
	v_sub_f32_e32 v82, v82, v133
	v_sub_f32_e32 v113, v113, v133
	v_sub_f32_e32 v112, v112, v133
	v_sub_f32_e32 v111, v111, v133
	v_sub_f32_e32 v110, v110, v133
	v_sub_f32_e32 v109, v109, v133
	v_sub_f32_e32 v108, v108, v133
	v_sub_f32_e32 v107, v107, v133
	v_sub_f32_e32 v106, v106, v133
	v_sub_f32_e32 v105, v105, v133
	v_sub_f32_e32 v104, v104, v133
	v_sub_f32_e32 v103, v103, v133
	v_sub_f32_e32 v102, v102, v133
	v_sub_f32_e32 v101, v101, v133
	v_sub_f32_e32 v100, v100, v133
	v_sub_f32_e32 v99, v99, v133
	v_sub_f32_e32 v98, v98, v133
	v_sub_f32_e32 v65, v65, v133
	v_sub_f32_e32 v64, v64, v133
	v_sub_f32_e32 v63, v63, v133
	v_sub_f32_e32 v62, v62, v133
	v_sub_f32_e32 v61, v61, v133
	v_sub_f32_e32 v60, v60, v133
	v_sub_f32_e32 v59, v59, v133
	v_sub_f32_e32 v58, v58, v133
	v_sub_f32_e32 v57, v57, v133
	v_sub_f32_e32 v56, v56, v133
	v_sub_f32_e32 v55, v55, v133
	v_sub_f32_e32 v54, v54, v133
	v_sub_f32_e32 v53, v53, v133
	v_sub_f32_e32 v52, v52, v133
	v_sub_f32_e32 v51, v51, v133
	v_sub_f32_e32 v50, v50, v133
